# v20 + P2a: the two per-column bias loads behind the first workgroup barrier issued with the up-front load batch (no cold miss after the barrier)
# baseline (speedup 1.0000x reference)
.LBB0_226:
	v_mov_b32_e32 v20, v161
	v_ashrrev_i32_e32 v144, 6, v20
	v_lshlrev_b32_e32 v144, 3, v144
	v_add_u32_e32 v144, s28, v144
	v_subrev_u32_e32 v145, 51, v144
	v_and_b32_e32 v146, 0x7f8, v145
	v_cmp_ne_u32_e64 s[98:99], 0, v146
	v_and_b32_e32 v147, 63, v20
	v_lshlrev_b32_e32 v147, 1, v147
	v_mul_u32_u24_e32 v148, 0x2200, v145
	v_add3_u32 v148, v148, v147, s63
	v_cndmask_b32_e64 v149, 0, v240, s[98:99]
	v_sub_u32_e32 v149, v148, v149
	global_load_ushort v150, v149, s[16:17] offset:32
	global_load_ushort v151, v149, s[16:17] offset:160
	global_load_ushort v152, v148, s[16:17] offset:32
	global_load_ushort v153, v148, s[16:17] offset:160
	v_add_u32_e32 v148, 0x2200, v148
	global_load_ushort v154, v148, s[16:17] offset:32
	global_load_ushort v155, v148, s[16:17] offset:160
	v_add_u32_e32 v148, 0x2200, v148
	global_load_ushort v168, v148, s[16:17] offset:32
	global_load_ushort v169, v148, s[16:17] offset:160
	v_add_u32_e32 v148, 0x2200, v148
	global_load_ushort v170, v148, s[16:17] offset:32
	global_load_ushort v171, v148, s[16:17] offset:160
	v_add_u32_e32 v148, 0x2200, v148
	global_load_ushort v172, v148, s[16:17] offset:32
	global_load_ushort v173, v148, s[16:17] offset:160
	v_add_u32_e32 v148, 0x2200, v148
	global_load_ushort v176, v148, s[16:17] offset:32
	global_load_ushort v177, v148, s[16:17] offset:160
	v_add_u32_e32 v148, 0x2200, v148
	global_load_ushort v178, v148, s[16:17] offset:32
	global_load_ushort v179, v148, s[16:17] offset:160
	v_add_u32_e32 v148, 0x2200, v148
	global_load_ushort v180, v148, s[16:17] offset:32
	global_load_ushort v181, v148, s[16:17] offset:160
	v_mov_b32_e32 v9, v3
	v_ashrrev_i32_e32 v38, 6, v20
	v_and_b32_e32 v183, 15, v20
	v_readfirstlane_b32 s2, v38
	v_bfe_u32 v182, v20, 4, 2
	v_lshlrev_b32_e32 v36, 11, v182
	v_lshl_or_b32 v0, s2, 5, v183
	v_ashrrev_i32_e32 v1, 31, v0
	v_or_b32_e32 v8, 0x400, v36
	v_lshl_add_u64 v[8:9], v[0:1], 0, v[8:9]
	v_lshlrev_b64 v[10:11], 2, v[8:9]
	v_lshl_add_u64 v[50:51], s[12:13], 0, v[10:11]
	v_lshl_add_u64 v[52:53], s[22:23], 0, v[10:11]
	v_or_b32_e32 v10, 0x500, v36
	v_mov_b32_e32 v11, v3
	v_lshl_add_u64 v[10:11], v[0:1], 0, v[10:11]
	v_lshlrev_b64 v[10:11], 2, v[10:11]
	v_lshl_add_u64 v[54:55], s[12:13], 0, v[10:11]
	v_lshl_add_u64 v[56:57], s[22:23], 0, v[10:11]
	v_or_b32_e32 v10, 0x600, v36
	v_mov_b32_e32 v11, v3
	v_lshl_add_u64 v[10:11], v[0:1], 0, v[10:11]
	v_lshlrev_b64 v[12:13], 2, v[10:11]
	v_lshl_add_u64 v[58:59], s[12:13], 0, v[12:13]
	v_lshl_add_u64 v[60:61], s[22:23], 0, v[12:13]
	v_or_b32_e32 v12, 0x700, v36
	v_mov_b32_e32 v13, v3
	v_lshl_add_u64 v[12:13], v[0:1], 0, v[12:13]
	v_or_b32_e32 v2, 0x2000, v36
	v_lshlrev_b64 v[12:13], 2, v[12:13]
	v_lshl_add_u64 v[62:63], s[12:13], 0, v[12:13]
	v_lshl_add_u64 v[64:65], s[22:23], 0, v[12:13]
	v_lshl_add_u64 v[12:13], v[0:1], 0, v[2:3]
	v_lshlrev_b64 v[14:15], 2, v[12:13]
	v_or_b32_e32 v2, 0x2100, v36
	v_lshl_add_u64 v[66:67], s[12:13], 0, v[14:15]
	v_lshl_add_u64 v[68:69], s[22:23], 0, v[14:15]
	v_lshl_add_u64 v[14:15], v[0:1], 0, v[2:3]
	v_lshlrev_b64 v[14:15], 2, v[14:15]
	v_or_b32_e32 v2, 0x2200, v36
	v_lshl_add_u64 v[70:71], s[12:13], 0, v[14:15]
	v_lshl_add_u64 v[72:73], s[22:23], 0, v[14:15]
	v_lshl_add_u64 v[14:15], v[0:1], 0, v[2:3]
	v_lshlrev_b64 v[16:17], 2, v[14:15]
	v_or_b32_e32 v2, 0x2300, v36
	v_lshl_add_u64 v[74:75], s[12:13], 0, v[16:17]
	v_lshl_add_u64 v[76:77], s[22:23], 0, v[16:17]
	v_lshl_add_u64 v[16:17], v[0:1], 0, v[2:3]
	v_lshlrev_b64 v[16:17], 2, v[16:17]
	v_or_b32_e32 v2, 0x2400, v36
	v_lshl_add_u64 v[78:79], s[12:13], 0, v[16:17]
	v_lshl_add_u64 v[80:81], s[22:23], 0, v[16:17]
	v_lshl_add_u64 v[16:17], v[0:1], 0, v[2:3]
	v_lshlrev_b64 v[18:19], 2, v[16:17]
	v_or_b32_e32 v2, 0x2500, v36
	v_lshl_add_u64 v[82:83], s[12:13], 0, v[18:19]
	v_lshl_add_u64 v[84:85], s[22:23], 0, v[18:19]
	v_lshl_add_u64 v[18:19], v[0:1], 0, v[2:3]
	v_lshlrev_b64 v[18:19], 2, v[18:19]
	v_or_b32_e32 v2, 0x2600, v36
	v_mov_b32_e32 v37, v3
	v_lshl_add_u64 v[86:87], s[12:13], 0, v[18:19]
	v_lshl_add_u64 v[88:89], s[22:23], 0, v[18:19]
	v_lshl_add_u64 v[18:19], v[0:1], 0, v[2:3]
	v_or_b32_e32 v2, 0x2700, v36
	v_lshl_add_u64 v[4:5], v[0:1], 0, v[36:37]
	v_or_b32_e32 v44, 0x100, v36
	v_or_b32_e32 v46, 0x200, v36
	v_or_b32_e32 v48, 0x300, v36
	v_lshl_add_u64 v[36:37], v[0:1], 0, v[2:3]
	v_lshlrev_b64 v[6:7], 2, v[4:5]
	v_lshlrev_b64 v[90:91], 2, v[18:19]
	v_lshlrev_b64 v[36:37], 2, v[36:37]
	v_lshl_add_u64 v[40:41], s[12:13], 0, v[6:7]
	v_lshl_add_u64 v[42:43], s[22:23], 0, v[6:7]
	v_mov_b32_e32 v45, v3
	v_lshl_add_u64 v[92:93], s[12:13], 0, v[90:91]
	v_lshl_add_u64 v[90:91], s[22:23], 0, v[90:91]
	v_lshl_add_u64 v[94:95], s[12:13], 0, v[36:37]
	v_lshl_add_u64 v[96:97], s[22:23], 0, v[36:37]
	v_add_u32_e32 v184, s84, v0
	v_ashrrev_i32_e32 v185, 31, v184
	v_lshlrev_b64 v[184:185], 2, v[184:185]
	v_lshl_add_u64 v[186:187], s[10:11], 0, v[184:185]
	v_lshl_add_u64 v[188:189], s[14:15], 0, v[184:185]
	global_load_dword v192, v[186:187], off
	global_load_dword v193, v[188:189], off
	global_load_dword v4, v[40:41], off
	global_load_dword v21, v[42:43], off
	global_load_dword v5, v[40:41], off offset:1024
	global_load_dword v22, v[42:43], off offset:1024
	global_load_dword v6, v[40:41], off offset:2048
	global_load_dword v23, v[42:43], off offset:2048
	global_load_dword v7, v[40:41], off offset:3072
	global_load_dword v24, v[42:43], off offset:3072
	global_load_dword v8, v[50:51], off
	global_load_dword v25, v[52:53], off
	global_load_dword v9, v[54:55], off
	global_load_dword v26, v[56:57], off
	global_load_dword v10, v[58:59], off
	global_load_dword v27, v[60:61], off
	global_load_dword v11, v[62:63], off
	global_load_dword v28, v[64:65], off
	global_load_dword v12, v[66:67], off
	global_load_dword v29, v[68:69], off
	global_load_dword v13, v[70:71], off
	global_load_dword v30, v[72:73], off
	global_load_dword v14, v[74:75], off
	global_load_dword v31, v[76:77], off
	global_load_dword v15, v[78:79], off
	global_load_dword v32, v[80:81], off
	global_load_dword v16, v[82:83], off
	global_load_dword v33, v[84:85], off
	global_load_dword v17, v[86:87], off
	global_load_dword v34, v[88:89], off
	global_load_dword v35, v[90:91], off
	global_load_dword v18, v[92:93], off
	global_load_dword v19, v[94:95], off
	global_load_dword v36, v[96:97], off
	global_load_dword v118, v[40:41], off offset:64
	global_load_dword v217, v[42:43], off offset:64
	v_lshl_add_u64 v[40:41], v[0:1], 0, v[44:45]
	v_lshlrev_b64 v[40:41], 2, v[40:41]
	v_mov_b32_e32 v47, v3
	v_lshl_add_u64 v[42:43], s[12:13], 0, v[40:41]
	v_lshl_add_u64 v[40:41], s[22:23], 0, v[40:41]
	global_load_dword v224, v[40:41], off offset:64
	v_lshl_add_u64 v[40:41], v[0:1], 0, v[46:47]
	v_lshlrev_b64 v[40:41], 2, v[40:41]
	v_mov_b32_e32 v49, v3
	global_load_dword v119, v[42:43], off offset:64
	v_lshl_add_u64 v[42:43], s[12:13], 0, v[40:41]
	v_lshl_add_u64 v[40:41], s[22:23], 0, v[40:41]
	global_load_dword v225, v[40:41], off offset:64
	v_lshl_add_u64 v[40:41], v[0:1], 0, v[48:49]
	v_and_b32_e32 v117, 63, v20
	v_lshlrev_b64 v[40:41], 2, v[40:41]
	global_load_dword v122, v[42:43], off offset:64
	v_lshl_add_u64 v[42:43], s[12:13], 0, v[40:41]
	v_lshl_add_u64 v[40:41], s[22:23], 0, v[40:41]
	v_lshlrev_b32_e32 v2, 2, v117
	global_load_dword v123, v[42:43], off offset:64
	global_load_dword v243, v[40:41], off offset:64
	global_load_dword v134, v[50:51], off offset:64
	global_load_dword v228, v[52:53], off offset:64
	global_load_dword v135, v[54:55], off offset:64
	global_load_dword v242, v[56:57], off offset:64
	global_load_dword v132, v[58:59], off offset:64
	global_load_dword v226, v[60:61], off offset:64
	global_load_dword v133, v[62:63], off offset:64
	global_load_dword v229, v[64:65], off offset:64
	global_load_dword v130, v[66:67], off offset:64
	global_load_dword v222, v[68:69], off offset:64
	global_load_dword v131, v[70:71], off offset:64
	global_load_dword v227, v[72:73], off offset:64
	global_load_dword v128, v[74:75], off offset:64
	global_load_dword v220, v[76:77], off offset:64
	global_load_dword v129, v[78:79], off offset:64
	global_load_dword v223, v[80:81], off offset:64
	global_load_dword v126, v[82:83], off offset:64
	global_load_dword v218, v[84:85], off offset:64
	global_load_dword v127, v[86:87], off offset:64
	global_load_dword v221, v[88:89], off offset:64
	global_load_dword v124, v[92:93], off offset:64
	global_load_dword v216, v[90:91], off offset:64
	global_load_dword v125, v[94:95], off offset:64
	global_load_dword v219, v[96:97], off offset:64
	global_load_dword v39, v2, s[24:25] offset:3072
	global_load_dword v37, v2, s[24:25] offset:3328
	v_and_b32_e32 v20, 48, v20
	s_waitcnt vmcnt(62)
	v_cvt_pk_bf16_f32 v76, v4, v5
	s_waitcnt vmcnt(59)
	v_cvt_pk_bf16_f32 v77, v6, v7
	s_waitcnt vmcnt(55)
	v_cvt_pk_bf16_f32 v78, v8, v9
	v_cvt_pk_bf16_f32 v88, v21, v22
	v_cvt_pk_bf16_f32 v89, v23, v24
	s_waitcnt vmcnt(54)
	v_cvt_pk_bf16_f32 v90, v25, v26
	s_waitcnt vmcnt(51)
	v_cvt_pk_bf16_f32 v79, v10, v11
	s_waitcnt vmcnt(50)
	v_cvt_pk_bf16_f32 v91, v27, v28
	s_waitcnt vmcnt(47)
	v_cvt_pk_bf16_f32 v108, v12, v13
	s_waitcnt vmcnt(46)
	v_cvt_pk_bf16_f32 v100, v29, v30
	s_waitcnt vmcnt(43)
	v_cvt_pk_bf16_f32 v109, v14, v15
	s_waitcnt vmcnt(42)
	v_cvt_pk_bf16_f32 v101, v31, v32
	s_waitcnt vmcnt(39)
	v_cvt_pk_bf16_f32 v110, v16, v17
	s_waitcnt vmcnt(38)
	v_cvt_pk_bf16_f32 v102, v33, v34
	s_waitcnt vmcnt(34)
	v_cvt_pk_bf16_f32 v103, v35, v36
	v_cvt_pk_bf16_f32 v111, v18, v19
	v_lshlrev_b32_e32 v43, 16, v150
	v_cndmask_b32_e64 v56, 0, v43, s[98:99]
	s_waitcnt vmcnt(0)
	v_lshlrev_b32_e32 v40, 16, v151
	v_cndmask_b32_e64 v54, 0, v40, s[98:99]
	s_nop 1
	v_lshlrev_b32_e32 v53, 16, v153
	v_lshlrev_b32_e32 v55, 16, v152
	v_sub_f32_e32 v56, v56, v55
	v_sub_f32_e32 v54, v54, v53
	v_fma_f32 v56, v39, v56, v55
	v_fma_f32 v54, v37, v54, v53
	v_add_f32_e32 v56, v56, v56
	v_cvt_pk_bf16_f32 v54, v54, s0
	v_mul_f32_e32 v56, 0xbfb8aa3b, v56
	v_exp_f32_e32 v56, v56
	v_lshlrev_b32_e32 v51, 16, v154
	v_add_f32_e32 v56, 1.0, v56
	v_lshlrev_b32_e32 v50, 16, v155
	v_sub_f32_e32 v53, v53, v50
	s_nop 0
	v_fma_f32 v53, v37, v53, v50
	v_rcp_f32_e32 v56, v56
	v_cvt_pk_bf16_f32 v53, v53, s0
	v_fma_f32 v56, v56, 2.0, -1.0
	v_cvt_pk_bf16_f32 v57, v56, v56
	v_lshlrev_b32_e32 v49, 16, v169
	v_lshlrev_b32_e32 v52, 16, v168
	v_sub_f32_e32 v50, v50, v49
	v_fma_f32 v50, v37, v50, v49
	v_cvt_pk_bf16_f32 v50, v50, s0
	v_lshlrev_b32_e32 v48, 16, v170
	v_lshlrev_b32_e32 v46, 16, v171
	v_sub_f32_e32 v49, v49, v46
	s_nop 0
	v_fma_f32 v49, v37, v49, v46
	v_cvt_pk_bf16_f32 v49, v49, s0
	v_lshlrev_b32_e32 v45, 16, v173
	s_nop 0
	v_lshlrev_b32_e32 v47, 16, v172
	v_sub_f32_e32 v46, v46, v45
	v_fma_f32 v46, v37, v46, v45
	v_cvt_pk_bf16_f32 v46, v46, s0
	v_lshlrev_b32_e32 v42, 16, v176
	v_lshlrev_b32_e32 v41, 16, v177
	s_nop 0
	s_nop 0
	s_movk_i32 s2, 0x240
	v_mul_lo_u32 v38, v38, s2
	v_or_b32_e32 v38, v38, v117
	v_lshl_add_u32 v38, v38, 1, 0
	ds_write_b16 v38, v54 offset:18432
	v_sub_f32_e32 v54, v55, v51
	v_fma_f32 v54, v39, v54, v51
	v_add_f32_e32 v54, v54, v54
	v_mul_f32_e32 v54, 0xbfb8aa3b, v54
	v_sub_f32_e32 v51, v51, v52
	v_exp_f32_e32 v54, v54
	v_fma_f32 v51, v39, v51, v52
	v_add_f32_e32 v51, v51, v51
	v_mul_f32_e32 v51, 0xbfb8aa3b, v51
	v_exp_f32_e32 v51, v51
	ds_write_b16 v38, v50 offset:18720
	v_sub_f32_e32 v50, v52, v48
	v_add_f32_e32 v54, 1.0, v54
	v_fma_f32 v50, v39, v50, v48
	v_rcp_f32_e32 v54, v54
	v_add_f32_e32 v50, v50, v50
	v_mul_f32_e32 v50, 0xbfb8aa3b, v50
	v_sub_f32_e32 v48, v48, v47
	v_add_f32_e32 v51, 1.0, v51
	v_exp_f32_e32 v50, v50
	v_fma_f32 v48, v39, v48, v47
	v_rcp_f32_e32 v51, v51
	v_add_f32_e32 v48, v48, v48
	v_sub_f32_e32 v45, v45, v41
	v_fma_f32 v54, v54, 2.0, -1.0
	v_mul_f32_e32 v48, 0xbfb8aa3b, v48
	ds_write_b16 v38, v46 offset:19008
	v_sub_f32_e32 v46, v47, v42
	v_fma_f32 v45, v37, v45, v41
	v_cvt_pk_bf16_f32 v55, v54, v54
	v_exp_f32_e32 v48, v48
	v_fma_f32 v46, v39, v46, v42
	v_add_f32_e32 v50, 1.0, v50
	v_add_f32_e32 v46, v46, v46
	v_fma_f32 v51, v51, 2.0, -1.0
	v_rcp_f32_e32 v50, v50
	v_mul_f32_e32 v46, 0xbfb8aa3b, v46
	ds_write_b16 v38, v53 offset:18576
	v_cvt_pk_bf16_f32 v53, v51, v51
	v_exp_f32_e32 v46, v46
	v_add_f32_e32 v48, 1.0, v48
	v_rcp_f32_e32 v48, v48
	v_fma_f32 v50, v50, 2.0, -1.0
	v_add_f32_e32 v46, 1.0, v46
	v_rcp_f32_e32 v46, v46
	v_fma_f32 v48, v48, 2.0, -1.0
	ds_write_b16 v38, v49 offset:18864
	v_cvt_pk_bf16_f32 v49, v48, v48
	v_fma_f32 v46, v46, 2.0, -1.0
	v_cvt_pk_bf16_f32 v47, v46, v46
	v_cvt_pk_bf16_f32 v45, v45, s0
	ds_write_b16 v38, v45 offset:19152
	ds_write_b16 v38, v57
	ds_write_b16 v38, v55 offset:144
	ds_write_b16 v38, v53 offset:288
	ds_write_b16 v38, v49 offset:576
	ds_write_b16 v38, v47 offset:720
	v_lshlrev_b32_e32 v44, 16, v178
	v_sub_f32_e32 v42, v42, v44
	v_fma_f32 v42, v39, v42, v44
	v_lshlrev_b32_e32 v43, 16, v180
	v_lshlrev_b32_e32 v40, 16, v179
	v_lshlrev_b32_e32 v58, 16, v57
	v_sub_f32_e32 v56, v56, v58
	v_sub_f32_e32 v41, v41, v40
	v_cvt_pk_bf16_f32 v56, v56, s0
	v_fma_f32 v41, v37, v41, v40
	ds_write_b16 v38, v56 offset:9216
	v_lshlrev_b32_e32 v56, 16, v55
	v_cvt_pk_bf16_f32 v41, v41, s0
	v_sub_f32_e32 v54, v54, v56
	ds_write_b16 v38, v41 offset:19296
	v_sub_f32_e32 v41, v44, v43
	v_cvt_pk_bf16_f32 v54, v54, s0
	v_fmac_f32_e32 v43, v39, v41
	ds_write_b16 v38, v54 offset:9360
	v_lshlrev_b32_e32 v54, 16, v53
	v_add_f32_e32 v42, v42, v42
	v_add_f32_e32 v39, v43, v43
	v_sub_f32_e32 v51, v51, v54
	v_mul_f32_e32 v42, 0xbfb8aa3b, v42
	v_mul_f32_e32 v39, 0xbfb8aa3b, v39
	v_cvt_pk_bf16_f32 v51, v51, s0
	v_exp_f32_e32 v42, v42
	v_exp_f32_e32 v39, v39
	ds_write_b16 v38, v51 offset:9504
	v_cvt_pk_bf16_f32 v51, v50, v50
	v_lshlrev_b32_e32 v52, 16, v51
	v_sub_f32_e32 v50, v50, v52
	v_cvt_pk_bf16_f32 v50, v50, s0
	v_add_f32_e32 v42, 1.0, v42
	v_add_f32_e32 v39, 1.0, v39
	ds_write_b16 v38, v50 offset:9648
	v_lshlrev_b32_e32 v50, 16, v49
	v_rcp_f32_e32 v42, v42
	v_rcp_f32_e32 v39, v39
	v_sub_f32_e32 v48, v48, v50
	v_cvt_pk_bf16_f32 v48, v48, s0
	ds_write_b16 v38, v48 offset:9792
	v_lshlrev_b32_e32 v48, 16, v47
	v_sub_f32_e32 v46, v46, v48
	v_fma_f32 v42, v42, 2.0, -1.0
	v_fma_f32 v39, v39, 2.0, -1.0
	v_cvt_pk_bf16_f32 v46, v46, s0
	v_cvt_pk_bf16_f32 v45, v42, v42
	ds_write_b16 v38, v46 offset:9936
	v_lshlrev_b32_e32 v46, 16, v45
	v_sub_f32_e32 v42, v42, v46
	v_cvt_pk_bf16_f32 v42, v42, s0
	ds_write_b16 v38, v51 offset:432
	ds_write_b16 v38, v45 offset:864
	ds_write_b16 v38, v42 offset:10080
	v_lshlrev_b32_e32 v2, 16, v181
	v_sub_f32_e32 v40, v40, v2
	v_fmac_f32_e32 v2, v37, v40
	v_cvt_pk_bf16_f32 v37, v39, v39
	v_lshlrev_b32_e32 v40, 16, v37
	ds_write_b16 v38, v37 offset:1008
	v_sub_f32_e32 v37, v39, v40
	v_cvt_pk_bf16_f32 v37, v37, s0
	v_cvt_pk_bf16_f32 v2, v2, s0
	ds_write_b16 v38, v37 offset:10224
	ds_write_b16 v38, v2 offset:19440
	v_lshlrev_b32_e32 v38, 16, v76
	v_and_b32_e32 v39, 0xffff0000, v76
	v_pk_add_f32 v[4:5], v[4:5], v[38:39] neg_lo:[0,1] neg_hi:[0,1]
	s_waitcnt lgkmcnt(0)
	v_cvt_pk_bf16_f32 v96, v4, v5
	v_lshlrev_b32_e32 v4, 16, v77
	v_and_b32_e32 v5, 0xffff0000, v77
	v_pk_add_f32 v[4:5], v[6:7], v[4:5] neg_lo:[0,1] neg_hi:[0,1]
	s_barrier
	v_cvt_pk_bf16_f32 v97, v4, v5
	v_lshlrev_b32_e32 v4, 16, v78
	v_and_b32_e32 v5, 0xffff0000, v78
	v_pk_add_f32 v[4:5], v[8:9], v[4:5] neg_lo:[0,1] neg_hi:[0,1]
	s_nop 0
	v_cvt_pk_bf16_f32 v98, v4, v5
	v_lshlrev_b32_e32 v4, 16, v79
	v_and_b32_e32 v5, 0xffff0000, v79
	v_pk_add_f32 v[4:5], v[10:11], v[4:5] neg_lo:[0,1] neg_hi:[0,1]
	s_nop 0
	v_cvt_pk_bf16_f32 v99, v4, v5
	v_lshlrev_b32_e32 v4, 16, v108
	v_and_b32_e32 v5, 0xffff0000, v108
	v_pk_add_f32 v[4:5], v[12:13], v[4:5] neg_lo:[0,1] neg_hi:[0,1]
	s_nop 0
	v_cvt_pk_bf16_f32 v104, v4, v5
	v_lshlrev_b32_e32 v4, 16, v109
	v_and_b32_e32 v5, 0xffff0000, v109
	v_pk_add_f32 v[4:5], v[14:15], v[4:5] neg_lo:[0,1] neg_hi:[0,1]
	s_nop 0
	v_cvt_pk_bf16_f32 v105, v4, v5
	v_lshlrev_b32_e32 v4, 16, v110
	v_and_b32_e32 v5, 0xffff0000, v110
	v_pk_add_f32 v[4:5], v[16:17], v[4:5] neg_lo:[0,1] neg_hi:[0,1]
	s_nop 0
	v_cvt_pk_bf16_f32 v106, v4, v5
	v_lshlrev_b32_e32 v4, 16, v111
	v_and_b32_e32 v5, 0xffff0000, v111
	v_pk_add_f32 v[4:5], v[18:19], v[4:5] neg_lo:[0,1] neg_hi:[0,1]
	s_nop 0
	v_cvt_pk_bf16_f32 v107, v4, v5
	v_add_u32_e32 v4, s84, v0
	v_ashrrev_i32_e32 v5, 31, v4
	v_lshlrev_b64 v[4:5], 2, v[4:5]
	v_lshl_add_u64 v[140:141], s[10:11], 0, v[4:5]
	v_mov_b32_e32 v2, v192
	v_lshl_add_u64 v[136:137], s[14:15], 0, v[4:5]
	v_mov_b32_e32 v190, v193
	v_mul_u32_u24_e32 v4, 0x48, v183
	v_lshlrev_b32_e32 v4, 1, v4
	v_add3_u32 v174, 0, v20, v4
	ds_read_b128 v[4:7], v174
	ds_read_b128 v[20:23], v174 offset:9216
	ds_read_b128 v[8:11], v174 offset:18432
	s_waitcnt lgkmcnt(2)
	v_mfma_f32_16x16x32_bf16 v[12:15], v[4:7], v[76:79], 0
	s_waitcnt lgkmcnt(1)
	v_mfma_f32_16x16x32_bf16 v[12:15], v[20:23], v[76:79], v[12:15]
	v_mfma_f32_16x16x32_bf16 v[28:31], v[4:7], v[96:99], v[12:15]
	s_nop 6
	ds_read_b128 v[12:15], v174 offset:64
	ds_read_b128 v[24:27], v174 offset:9280
	ds_read_b128 v[16:19], v174 offset:18496
	s_waitcnt lgkmcnt(2)
	v_mfma_f32_16x16x32_bf16 v[28:31], v[12:15], v[108:111], v[28:31]
	s_waitcnt lgkmcnt(1)
	v_mfma_f32_16x16x32_bf16 v[28:31], v[24:27], v[108:111], v[28:31]
	v_mfma_f32_16x16x32_bf16 v[36:39], v[8:11], v[88:91], 0
	v_mfma_f32_16x16x32_bf16 v[32:35], v[12:15], v[104:107], v[28:31]
	s_waitcnt lgkmcnt(0)
	v_mfma_f32_16x16x32_bf16 v[28:31], v[16:19], v[100:103], v[36:39]
	s_waitcnt vmcnt(1)
	s_nop 4
	v_add_f32_e32 v32, v2, v32
	v_cmp_ngt_f32_e32 vcc, s74, v32
	v_xor_b32_e32 v191, 0x80000000, v32
	s_and_saveexec_b64 s[2:3], vcc
	s_xor_b64 s[4:5], exec, s[2:3]
	s_cbranch_execz .LBB0_228
	v_mul_f32_e32 v32, 0xbfb8aa3b, v32
	v_exp_f32_e32 v32, v32
	s_nop 0
	v_add_f32_e32 v32, 1.0, v32
	v_cmp_gt_f32_e32 vcc, s75, v32
	s_nop 1
	v_cndmask_b32_e64 v36, 0, 32, vcc
	v_ldexp_f32 v32, v32, v36
	v_log_f32_e32 v32, v32
	s_nop 0
	v_mul_f32_e32 v36, 0x3f317217, v32
	v_fma_f32 v36, v32, s88, -v36
	v_fmac_f32_e32 v36, 0x3377d1cf, v32
	v_fmac_f32_e32 v36, 0x3f317217, v32
	v_cmp_lt_f32_e64 s[2:3], |v32|, s70
	s_nop 1
	v_cndmask_b32_e64 v32, v32, v36, s[2:3]
	v_cndmask_b32_e32 v36, 0, v233, vcc
	v_sub_f32_e32 v191, v32, v36
